# prologue shortened: layer-0 w_gate_up tail + w_down conversion deferred to the idle workgroups of layer 0's in-projection tail (own work counter); adaLN item loads batched/prefetched
# speedup vs baseline: 1.0290x; 1.0083x over previous
.LBB0_84:
	s_or_b64 exec, exec, s[2:3]
	s_add_i32 s46, 0, 0x20180
	v_mov_b32_e32 v1, s46
	s_waitcnt lgkmcnt(0)
	s_barrier
	ds_read_b32 v1, v1
	s_mov_b32 s21, 0
	s_waitcnt lgkmcnt(0)
	v_readfirstlane_b32 s47, v1
	s_cmpk_gt_i32 s47, 0x5ff
	s_cbranch_scc1 .LBB0_147
	s_ashr_i32 s2, s22, 6
	v_bfe_u32 v3, v2, 5, 1
	v_and_b32_e32 v4, 31, v2
	v_lshlrev_b32_e32 v1, 1, v3
	s_lshl_b32 s3, s2, 3
	v_lshlrev_b32_e32 v3, 2, v3
	v_lshlrev_b32_e32 v54, 2, v4
	v_lshlrev_b32_e32 v55, 10, v4
	v_lshlrev_b32_e32 v4, 3, v4
	v_or_b32_e32 v5, s3, v3
	v_bitop3_b32 v57, s3, v4, v3 bitop3:0x36
	v_add_u32_e32 v3, 64, v5
	v_xor_b32_e32 v58, v3, v4
	v_add_u32_e32 v3, 0x80, v5
	v_xor_b32_e32 v59, v3, v4
	v_add_u32_e32 v3, 0xc0, v5
	v_lshl_or_b32 v1, s2, 2, v1
	s_lshl_b32 s4, s2, 4
	v_lshlrev_b32_e32 v7, 4, v2
	v_xor_b32_e32 v60, v3, v4
	s_lshl_b32 s2, s2, 5
	v_mov_b32_e32 v3, 0xf0
	v_bfe_u32 v6, v2, 4, 2
	v_bitop3_b32 v62, s2, v3, v7 bitop3:0x48
	s_or_b32 s2, s4, 8
	v_or_b32_e32 v4, s2, v6
	s_lshl_b32 s2, s2, 1
	v_bitop3_b32 v64, s2, v3, v7 bitop3:0x48
	s_or_b32 s2, s4, 12
	v_readlane_b32 s80, v250, 5
	v_lshlrev_b32_e32 v63, 8, v4
	v_or_b32_e32 v4, s2, v6
	s_lshl_b32 s2, s2, 1
	v_readlane_b32 s94, v250, 19
	v_readlane_b32 s95, v250, 20
	s_add_u32 s22, s94, 0x14400000
	s_addc_u32 s23, s95, 0
	s_add_u32 s24, s94, 0x9400000
	v_lshlrev_b32_e32 v2, 3, v2
	s_addc_u32 s25, s95, 0
	v_or_b32_e32 v56, s4, v6
	v_and_b32_e32 v2, 0x78, v2
	s_add_u32 s26, s94, 0x7400000
	v_mov_b32_e32 v51, 0
	v_lshlrev_b32_e32 v61, 8, v56
	v_lshlrev_b32_e32 v65, 8, v4
	v_bitop3_b32 v66, s2, v3, v7 bitop3:0x48
	s_addc_u32 s27, s95, 0
	v_lshlrev_b32_e32 v50, 1, v2
	v_mov_b32_e32 v67, 0x80
	v_mov_b32_e32 v68, 10
	v_mov_b32_e32 v69, 5
	v_mov_b32_e32 v70, 7
	s_mov_b32 s48, 0
	v_readlane_b32 s81, v250, 6
	v_readlane_b32 s82, v250, 7
	v_readlane_b32 s83, v250, 8
	v_readlane_b32 s84, v250, 9
	v_readlane_b32 s85, v250, 10
	v_readlane_b32 s86, v250, 11
	v_readlane_b32 s87, v250, 12
	v_readlane_b32 s88, v250, 13
	v_readlane_b32 s89, v250, 14
	v_readlane_b32 s90, v250, 15
	v_readlane_b32 s91, v250, 16
	v_readlane_b32 s92, v250, 17
	v_readlane_b32 s93, v250, 18
	s_branch .LBB0_87
.LBB0_86:
	s_or_b64 exec, exec, s[2:3]
	s_waitcnt vmcnt(0)
	v_mov_b32_e32 v2, s46
	s_waitcnt lgkmcnt(0)
	s_barrier
	ds_read_b32 v2, v2
	s_waitcnt lgkmcnt(0)
	v_readfirstlane_b32 s47, v2
	s_cmpk_lt_i32 s47, 0x600
	s_cbranch_scc0 .LBB0_147

.LBB0_91:
	s_or_b64 exec, exec, s[2:3]
	s_sub_i32 s2, 0x600, s47
	s_min_i32 s49, s2, 4
	s_max_i32 s2, s49, 1
	v_mov_b32_e32 v2, 0
	s_mov_b32 s50, 1
	s_lshl_b32 s51, s2, 3
	s_lshl_b32 s52, s47, 7
	s_lshl_b32 s53, s47, 3
	s_mov_b64 s[30:31], 0
	s_mov_b32 s54, 0
	v_mov_b32_e32 v3, v2
	v_mov_b32_e32 v4, v2
	v_mov_b32_e32 v5, v2
	v_mov_b32_e32 v10, v2
	v_mov_b32_e32 v11, v2
	v_mov_b32_e32 v12, v2
	v_mov_b32_e32 v13, v2
	v_mov_b32_e32 v18, v2
	v_mov_b32_e32 v19, v2
	v_mov_b32_e32 v20, v2
	v_mov_b32_e32 v21, v2
	v_mov_b32_e32 v26, v2
	v_mov_b32_e32 v27, v2
	v_mov_b32_e32 v28, v2
	v_mov_b32_e32 v29, v2
	v_mov_b32_e32 v6, v2
	v_mov_b32_e32 v7, v2
	v_mov_b32_e32 v8, v2
	v_mov_b32_e32 v9, v2
	v_mov_b32_e32 v14, v2
	v_mov_b32_e32 v15, v2
	v_mov_b32_e32 v16, v2
	v_mov_b32_e32 v17, v2
	v_mov_b32_e32 v22, v2
	v_mov_b32_e32 v23, v2
	v_mov_b32_e32 v24, v2
	v_mov_b32_e32 v25, v2
	v_mov_b32_e32 v30, v2
	v_mov_b32_e32 v31, v2
	v_mov_b32_e32 v32, v2
	v_mov_b32_e32 v33, v2
	s_branch .LBB0_93

.LBB0_406:
	v_readlane_b32 s0, v255, 2
	s_cmp_eq_u32 s0, 3
	v_readlane_b32 s1, v255, 3
	s_cbranch_scc1 .LBB0_469
	v_readlane_b32 s0, v253, 48
	v_readlane_b32 s1, v253, 49
	s_andn2_b64 vcc, exec, s[0:1]
	s_cbranch_vccnz .LBB0_469
	v_readlane_b32 s0, v255, 2
	v_readlane_b32 s8, v250, 5
	v_readlane_b32 s1, v255, 3
	v_mov_b32_e32 v2, v0
	v_readlane_b32 s9, v250, 6
	v_readlane_b32 s10, v250, 7
	v_readlane_b32 s11, v250, 8
	v_readlane_b32 s14, v250, 11
	v_readlane_b32 s15, v250, 12
	v_readlane_b32 s16, v250, 13
	v_readlane_b32 s17, v250, 14
	v_readlane_b32 s18, v250, 15
	v_readlane_b32 s19, v250, 16
	s_add_i32 s0, s0, 1
	s_cmp_eq_u32 s0, 1
	s_cselect_b32 s0, 0, s0
	v_readlane_b32 s12, v250, 9
	v_readfirstlane_b32 s1, v2
	v_readlane_b32 s13, v250, 10
	s_mov_b64 s[10:11], s[14:15]
	s_mov_b64 s[4:5], s[18:19]
	s_mov_b64 s[2:3], s[62:63]
	s_mov_b64 s[8:9], s[16:17]
	v_cmp_eq_u32_e32 vcc, 0, v2
	v_readlane_b32 s20, v250, 17
	v_readlane_b32 s21, v250, 18
	v_readlane_b32 s22, v250, 19
	v_readlane_b32 s23, v250, 20
	s_waitcnt vmcnt(0)
	s_barrier
	s_and_saveexec_b64 s[12:13], vcc
	s_cbranch_execz .LBB0_412
	s_mov_b64 s[16:17], exec
	v_mbcnt_lo_u32_b32 v3, s16, 0
	v_mbcnt_hi_u32_b32 v3, s17, v3
	v_cmp_eq_u32_e32 vcc, 0, v3
	s_and_saveexec_b64 s[14:15], vcc
	s_cbranch_execz .LBB0_411
	s_lshl_b32 s28, s0, 6
	s_lshl_b64 s[18:19], s[28:29], 2
	v_readlane_b32 s20, v252, 11
	s_add_u32 s18, s20, s18
	v_readlane_b32 s20, v252, 12
	s_addc_u32 s19, s20, s19
	v_readlane_b32 s20, v255, 2
	s_cmp_eq_u32 s20, 0
	s_cselect_b32 s20, 0x80, 0
	s_add_u32 s18, s18, s20
	s_addc_u32 s19, s19, 0
	s_bcnt1_i32_b64 s16, s[16:17]
	v_readlane_b32 s20, v255, 2
	s_cmp_eq_u32 s20, 0
	s_cselect_b32 s20, 13, 5
	s_mul_i32 s16, s16, s20
	s_waitcnt lgkmcnt(1)
	v_mov_b32_e32 v4, s16
	global_atomic_add v4, v67, v4, s[18:19] sc0

.LBB0_412:
	s_or_b64 exec, exec, s[12:13]
	v_readlane_b32 s12, v254, 19
	s_waitcnt lgkmcnt(0)
	s_barrier
	v_mov_b32_e32 v3, s12
	ds_read_b32 v3, v3
	s_waitcnt lgkmcnt(0)
	v_readfirstlane_b32 s25, v3
	v_readlane_b32 s12, v255, 2
	s_cmp_eq_u32 s12, 0
	s_cselect_b32 s12, 0x600, 0
	s_add_i32 s25, s25, s12
	s_cmpk_gt_i32 s25, 0xc3f
	s_cbranch_scc1 .LBB0_468
	s_ashr_i32 s14, s1, 6
	s_mul_i32 s16, s0, 0x2c00000
	s_mul_hi_u32 s17, s0, 0x2c00000
	s_add_u32 s4, s4, s16
	s_addc_u32 s5, s5, s17
	s_mul_i32 s13, s0, 0x5800000
	s_mov_b32 s1, s29
	s_mul_hi_u32 s12, s0, 0x5800000
	s_add_u32 s8, s8, s13
	s_addc_u32 s9, s9, s12
	s_lshl_b64 s[12:13], s[0:1], 24
	s_add_u32 s10, s10, s12
	s_addc_u32 s11, s11, s13
	s_mul_i32 s12, s0, 0x3000000
	v_bfe_u32 v3, v2, 5, 1
	s_mul_hi_u32 s13, s0, 0x3000000
	s_add_u32 s12, s2, s12
	s_addc_u32 s13, s3, s13
	v_lshlrev_b32_e32 v5, 1, v3
	s_lshl_b32 s2, s14, 3
	v_lshlrev_b32_e32 v3, 2, v3
	v_and_b32_e32 v4, 31, v2
	v_or_b32_e32 v6, s2, v3
	v_bfe_u32 v7, v2, 4, 2
	v_lshlrev_b32_e32 v8, 4, v2
	v_lshlrev_b32_e32 v2, 3, v2
	v_lshl_or_b32 v52, s14, 2, v5
	v_lshlrev_b32_e32 v53, 2, v4
	v_lshlrev_b32_e32 v54, 10, v4
	v_lshlrev_b32_e32 v5, 3, v4
	v_and_b32_e32 v4, 0x78, v2
	v_add_u32_e32 v2, 64, v6
	s_lshl_b32 s3, s14, 4
	v_bitop3_b32 v56, s2, v5, v3 bitop3:0x36
	v_xor_b32_e32 v57, v2, v5
	v_add_u32_e32 v2, 0x80, v6
	s_lshl_b32 s2, s14, 5
	v_mov_b32_e32 v3, 0xf0
	v_xor_b32_e32 v58, v2, v5
	v_add_u32_e32 v2, 0xc0, v6
	v_bitop3_b32 v61, s2, v3, v8 bitop3:0x48
	s_or_b32 s2, s3, 8
	v_xor_b32_e32 v59, v2, v5
	v_or_b32_e32 v2, s2, v7
	s_lshl_b32 s2, s2, 1
	s_sub_i32 s18, 0xc40, s25
	v_bitop3_b32 v63, s2, v3, v8 bitop3:0x48
	s_or_b32 s2, s3, 12
	v_readlane_b32 s51, v255, 2
	s_cmp_eq_u32 s51, 0
	s_cselect_b32 s51, 13, 5
	s_min_i32 s51, s18, s51
	v_lshlrev_b32_e32 v62, 8, v2
	v_or_b32_e32 v2, s2, v7
	s_lshl_b32 s2, s2, 1
	s_mul_i32 s14, s0, 0x1600000
	s_max_i32 s22, s51, 1
	v_readlane_b32 s18, v252, 13
	s_mul_hi_u32 s15, s0, 0x1600000
	s_add_u32 s14, s18, s14
	v_readlane_b32 s18, v252, 14
	s_addc_u32 s15, s18, s15
	v_readlane_b32 s18, v252, 15
	s_add_u32 s16, s18, s16
	v_readlane_b32 s18, v252, 16
	v_or_b32_e32 v55, s3, v7
	v_bitop3_b32 v65, s2, v3, v8 bitop3:0x48
	s_mul_hi_u32 s2, s0, 0x1b00000
	s_mul_i32 s3, s0, 0x1b00000
	s_addc_u32 s17, s18, s17
	s_lshl_b64 s[0:1], s[0:1], 23
	v_readlane_b32 s18, v252, 17
	s_add_u32 s18, s18, s0
	v_readlane_b32 s0, v252, 18
	s_addc_u32 s19, s0, s1
	v_readlane_b32 s0, v252, 1
	v_lshlrev_b32_e32 v64, 8, v2
	s_add_u32 s20, s0, s3
	v_readlane_b32 s0, v252, 2
	v_mov_b32_e32 v2, 0
	s_mov_b32 s50, 1
	v_lshlrev_b32_e32 v60, 8, v55
	s_addc_u32 s21, s0, s2
	s_lshl_b32 s52, s22, 3
	s_lshl_b32 s53, s25, 7
	s_lshl_b32 s54, s25, 3
	s_mov_b64 s[22:23], 0
	s_mov_b32 s55, 0
	v_lshlrev_b32_e32 v66, 1, v4
	s_mov_b32 s56, 0
	v_mov_b32_e32 v3, v2
	v_mov_b32_e32 v4, v2
	v_mov_b32_e32 v5, v2
	v_mov_b32_e32 v10, v2
	v_mov_b32_e32 v11, v2
	v_mov_b32_e32 v12, v2
	v_mov_b32_e32 v13, v2
	v_mov_b32_e32 v18, v2
	v_mov_b32_e32 v19, v2
	v_mov_b32_e32 v20, v2
	v_mov_b32_e32 v21, v2
	v_mov_b32_e32 v26, v2
	v_mov_b32_e32 v27, v2
	v_mov_b32_e32 v28, v2
	v_mov_b32_e32 v29, v2
	v_mov_b32_e32 v6, v2
	v_mov_b32_e32 v7, v2
	v_mov_b32_e32 v8, v2
	v_mov_b32_e32 v9, v2
	v_mov_b32_e32 v14, v2
	v_mov_b32_e32 v15, v2
	v_mov_b32_e32 v16, v2
	v_mov_b32_e32 v17, v2
	v_mov_b32_e32 v22, v2
	v_mov_b32_e32 v23, v2
	v_mov_b32_e32 v24, v2
	v_mov_b32_e32 v25, v2
	v_mov_b32_e32 v30, v2
	v_mov_b32_e32 v31, v2
	v_mov_b32_e32 v32, v2
	v_mov_b32_e32 v33, v2
	s_branch .LBB0_415
